# v27 with the K/Q part of the component-boundary prefetch issued earlier (behind the final step's bias block, before its PV phase); V0 stays behind the drain barrier
# speedup vs baseline: 1.0012x; 1.0012x over previous
.LBB0_1137:
	s_add_u32 s98, s44, 0x80
	s_addc_u32 s99, s45, 0
	s_mov_b32 m0, s33
	s_nop 0
	global_load_lds_dwordx4 v202, s[98:99]
	s_add_u32 s98, s44, 0x20080
	s_addc_u32 s99, s45, 0
	s_add_i32 m0, s33, 0x2000
	s_nop 0
	global_load_lds_dwordx4 v202, s[98:99]
	v_readfirstlane_b32 s98, v184
	s_nop 3
	s_ashr_i32 s98, s98, 6
	s_lshl_b32 s98, s98, 5
	s_add_i32 s98, s98, s77
	s_ashr_i32 s99, s98, 31
	s_lshl_b64 s[98:99], s[98:99], 11
	s_add_u32 s100, s75, s98
	s_addc_u32 s101, s76, s99
	v_and_b32_e32 v253, 31, v184
	v_bfe_u32 v254, v184, 5, 1
	v_lshlrev_b32_e32 v253, 11, v253
	v_lshl_or_b32 v253, v254, 4, v253
	global_load_dwordx4 v[158:161], v253, s[100:101] offset:128
	global_load_dwordx4 v[154:157], v253, s[100:101] offset:160
	global_load_dwordx4 v[150:153], v253, s[100:101] offset:192
	global_load_dwordx4 v[146:149], v253, s[100:101] offset:224
	s_add_u32 s98, s44, 0x40080
	s_addc_u32 s99, s45, 0
	s_add_i32 m0, s33, 0x4000
	s_nop 0
	global_load_lds_dwordx4 v202, s[98:99]
	v_add_f32_e32 v0, v178, v0
	v_mfma_f32_32x32x16_bf16 v[50:65], v[142:145], v[174:177], v[50:65]
	v_exp_f32_e32 v98, v98
	v_exp_f32_e32 v99, v99
	ds_read_b64_tr_b16 v[78:79], v179 offset:40960
	ds_read_b64_tr_b16 v[80:81], v179 offset:41472
	v_mfma_f32_32x32x16_bf16 v[34:49], v[142:145], v[82:85], v[34:49]
	v_exp_f32_e32 v100, v100
	v_exp_f32_e32 v101, v101
	ds_read_b64_tr_b16 v[82:83], v179 offset:45056
	ds_read_b64_tr_b16 v[84:85], v179 offset:45568
	v_mfma_f32_32x32x16_bf16 v[50:65], v[138:141], v[86:89], v[50:65]
	v_exp_f32_e32 v102, v102
	v_exp_f32_e32 v103, v103
	ds_read_b64_tr_b16 v[86:87], v179 offset:41984
	ds_read_b64_tr_b16 v[88:89], v179 offset:42496
	v_mfma_f32_32x32x16_bf16 v[34:49], v[138:141], v[90:93], v[34:49]
	v_exp_f32_e32 v104, v104
	v_exp_f32_e32 v105, v105
	ds_read_b64_tr_b16 v[90:91], v179 offset:46080
	ds_read_b64_tr_b16 v[92:93], v179 offset:46592
	s_waitcnt lgkmcnt(14)
	v_mfma_f32_32x32x16_bf16 v[50:65], v[134:137], v[94:97], v[50:65]
	v_exp_f32_e32 v106, v106
	v_exp_f32_e32 v107, v107
	ds_read_b64_tr_b16 v[94:95], v179 offset:43008
	ds_read_b64_tr_b16 v[96:97], v179 offset:43520
	s_waitcnt lgkmcnt(14)
	v_mfma_f32_32x32x16_bf16 v[34:49], v[134:137], v[66:69], v[34:49]
	v_exp_f32_e32 v108, v108
	v_exp_f32_e32 v109, v109
	ds_read_b64_tr_b16 v[66:67], v179 offset:47104
	ds_read_b64_tr_b16 v[68:69], v179 offset:47616
	s_waitcnt lgkmcnt(14)
	v_mfma_f32_32x32x16_bf16 v[50:65], v[130:133], v[70:73], v[50:65]
	v_exp_f32_e32 v110, v110
	v_exp_f32_e32 v111, v111
	ds_read_b64_tr_b16 v[70:71], v179 offset:44032
	ds_read_b64_tr_b16 v[72:73], v179 offset:44544
	s_waitcnt lgkmcnt(14)
	v_mfma_f32_32x32x16_bf16 v[34:49], v[130:133], v[74:77], v[34:49]
	v_exp_f32_e32 v112, v112
	v_exp_f32_e32 v113, v113
	ds_read_b64_tr_b16 v[74:75], v179 offset:48128
	ds_read_b64_tr_b16 v[76:77], v179 offset:48640
	s_waitcnt lgkmcnt(14)
	v_mfma_f32_32x32x16_bf16 v[18:33], v[142:145], v[78:81], v[18:33]
	v_exp_f32_e32 v114, v114
	v_exp_f32_e32 v115, v115
	s_waitcnt lgkmcnt(12)
	v_mfma_f32_32x32x16_bf16 v[2:17], v[142:145], v[82:85], v[2:17]
	v_exp_f32_e32 v116, v116
	v_exp_f32_e32 v117, v117
	s_waitcnt lgkmcnt(10)
	v_mfma_f32_32x32x16_bf16 v[18:33], v[138:141], v[86:89], v[18:33]
	v_exp_f32_e32 v118, v118
	v_exp_f32_e32 v119, v119
	s_waitcnt lgkmcnt(8)
	v_mfma_f32_32x32x16_bf16 v[2:17], v[138:141], v[90:93], v[2:17]
	v_exp_f32_e32 v120, v120
	v_exp_f32_e32 v121, v121
	s_waitcnt lgkmcnt(6)
	v_mfma_f32_32x32x16_bf16 v[18:33], v[134:137], v[94:97], v[18:33]
	v_exp_f32_e32 v122, v122
	v_exp_f32_e32 v123, v123
	s_waitcnt lgkmcnt(4)
	v_mfma_f32_32x32x16_bf16 v[2:17], v[134:137], v[66:69], v[2:17]
	v_exp_f32_e32 v124, v124
	v_exp_f32_e32 v125, v125
	s_waitcnt lgkmcnt(2)
	v_mfma_f32_32x32x16_bf16 v[18:33], v[130:133], v[70:73], v[18:33]
	v_exp_f32_e32 v126, v126
	v_exp_f32_e32 v127, v127
	s_waitcnt lgkmcnt(0)
	v_mfma_f32_32x32x16_bf16 v[2:17], v[130:133], v[74:77], v[2:17]
	v_exp_f32_e32 v128, v128
	v_exp_f32_e32 v129, v129
	s_cmp_eq_u32 s74, s57
	s_cselect_b64 s[8:9], -1, 0
	s_cmp_eq_u32 s58, s74
	s_cselect_b64 s[10:11], -1, 0
	s_or_b64 s[8:9], s[8:9], s[10:11]
	s_andn2_b64 vcc, exec, s[8:9]
	s_cbranch_vccnz .LBB0_1139
	s_cmp_lt_i32 s16, s57
	s_cselect_b64 vcc, -1, 0
	s_cmp_le_i32 s58, s16
	s_cselect_b64 s[8:9], -1, 0
	v_cndmask_b32_e64 v66, 0, v199, s[8:9]
	s_cmp_gt_i32 s69, s57
	v_cndmask_b32_e32 v66, v66, v198, vcc
	v_cndmask_b32_e64 v67, 0, v199, s[6:7]
	s_cselect_b64 vcc, -1, 0
	v_cndmask_b32_e32 v67, v198, v67, vcc
	v_sub_f32_e32 v66, v66, v67
	v_exp_f32_e32 v66, v66
	s_nop 0
	v_pk_mul_f32 v[64:65], v[66:67], v[64:65] op_sel_hi:[0,1]
	v_pk_mul_f32 v[62:63], v[66:67], v[62:63] op_sel_hi:[0,1]
	v_pk_mul_f32 v[60:61], v[66:67], v[60:61] op_sel_hi:[0,1]
	v_pk_mul_f32 v[58:59], v[66:67], v[58:59] op_sel_hi:[0,1]
	v_pk_mul_f32 v[56:57], v[66:67], v[56:57] op_sel_hi:[0,1]
	v_pk_mul_f32 v[54:55], v[66:67], v[54:55] op_sel_hi:[0,1]
	v_pk_mul_f32 v[52:53], v[66:67], v[52:53] op_sel_hi:[0,1]
	v_pk_mul_f32 v[50:51], v[66:67], v[50:51] op_sel_hi:[0,1]
	v_pk_mul_f32 v[48:49], v[66:67], v[48:49] op_sel_hi:[0,1]
	v_pk_mul_f32 v[46:47], v[66:67], v[46:47] op_sel_hi:[0,1]
	v_pk_mul_f32 v[44:45], v[66:67], v[44:45] op_sel_hi:[0,1]
	v_pk_mul_f32 v[42:43], v[66:67], v[42:43] op_sel_hi:[0,1]
	v_pk_mul_f32 v[40:41], v[66:67], v[40:41] op_sel_hi:[0,1]
	v_pk_mul_f32 v[38:39], v[66:67], v[38:39] op_sel_hi:[0,1]
	v_pk_mul_f32 v[36:37], v[66:67], v[36:37] op_sel_hi:[0,1]
	v_pk_mul_f32 v[34:35], v[66:67], v[34:35] op_sel_hi:[0,1]
	v_pk_mul_f32 v[32:33], v[66:67], v[32:33] op_sel_hi:[0,1]
	v_pk_mul_f32 v[30:31], v[66:67], v[30:31] op_sel_hi:[0,1]
	v_pk_mul_f32 v[28:29], v[66:67], v[28:29] op_sel_hi:[0,1]
	v_pk_mul_f32 v[26:27], v[66:67], v[26:27] op_sel_hi:[0,1]
	v_pk_mul_f32 v[24:25], v[66:67], v[24:25] op_sel_hi:[0,1]
	v_pk_mul_f32 v[22:23], v[66:67], v[22:23] op_sel_hi:[0,1]
	v_pk_mul_f32 v[20:21], v[66:67], v[20:21] op_sel_hi:[0,1]
	v_pk_mul_f32 v[18:19], v[66:67], v[18:19] op_sel_hi:[0,1]
	v_pk_mul_f32 v[16:17], v[66:67], v[16:17] op_sel_hi:[0,1]
	v_pk_mul_f32 v[14:15], v[66:67], v[14:15] op_sel_hi:[0,1]
	v_pk_mul_f32 v[12:13], v[66:67], v[12:13] op_sel_hi:[0,1]
	v_pk_mul_f32 v[10:11], v[66:67], v[10:11] op_sel_hi:[0,1]
	v_pk_mul_f32 v[8:9], v[66:67], v[8:9] op_sel_hi:[0,1]
	v_pk_mul_f32 v[6:7], v[66:67], v[6:7] op_sel_hi:[0,1]
	v_pk_mul_f32 v[4:5], v[66:67], v[4:5] op_sel_hi:[0,1]
	v_pk_mul_f32 v[2:3], v[66:67], v[2:3] op_sel_hi:[0,1]
	v_mul_f32_e32 v0, v66, v0
.LBB0_1139:
	s_cmp_lg_u32 s69, 32
	s_cbranch_scc1 .Lnbp_none
	s_waitcnt lgkmcnt(0)
	s_barrier
	s_add_i32 m0, s33, 0x8000
	s_nop 0
	global_load_lds_dwordx4 v203, s[46:47]
	s_add_i32 m0, s33, 0xa000
	s_nop 0
	global_load_lds_dwordx4 v203, s[48:49]
